# E1+T1 + P11 epilogue: x1 row loads of all rounds issued up front with counted waits
# speedup vs baseline: 1.0104x; 1.0104x over previous
.LBB0_801:
	v_lshl_or_b32 v56, s71, 8, v180
	v_lshl_add_u32 v174, s70, 8, v176
	v_lshlrev_b32_e32 v185, 2, v56
	v_lshl_add_u32 v184, v174, 12, v185
	s_ashr_i32 s8, s70, 5
	v_lshrrev_b32_e32 v57, 1, v184
	s_mul_hi_i32 s9, s8, 0x6000
	s_mulk_i32 s8, 0x6000
	global_load_dwordx4 v[186:189], v57, s[30:31]
	global_load_dwordx4 v[190:193], v57, s[30:31] offset:256
	v_add_u32_e32 v252, 0x8000, v57
	v_add_u32_e32 v254, 0x10000, v57
	v_add_u32_e32 v255, 0x18000, v57
	v_ashrrev_i32_e32 v57, 31, v56
	s_add_u32 s8, s58, s8
	v_lshlrev_b64 v[56:57], 2, v[56:57]
	s_addc_u32 s9, s59, s9
	v_lshl_add_u64 v[58:59], s[8:9], 0, v[56:57]
	global_load_dwordx4 v[156:159], v[58:59], off
	global_load_dwordx4 v[152:155], v[58:59], off offset:16
	global_load_dwordx4 v[148:151], v[58:59], off offset:512
	global_load_dwordx4 v[144:147], v[58:59], off offset:528
	v_lshl_add_u64 v[68:69], s[26:27], 0, v[56:57]
	global_load_dwordx4 v[72:75], v[68:69], off offset:16
	global_load_dwordx4 v[76:79], v[68:69], off
	global_load_dwordx4 v[56:59], v[68:69], off offset:528
	s_nop 0
	global_load_dwordx4 v[68:71], v[68:69], off offset:512
	global_load_dwordx4 v[202:205], v252, s[30:31]
	global_load_dwordx4 v[206:209], v252, s[30:31] offset:256
	global_load_dwordx4 v[210:213], v254, s[30:31]
	global_load_dwordx4 v[214:217], v254, s[30:31] offset:256
	global_load_dwordx4 v[218:221], v255, s[30:31]
	global_load_dwordx4 v[222:225], v255, s[30:31] offset:256
	v_add_u32_e32 v252, 0x38000, v252
	v_add_u32_e32 v254, 0x38000, v254
	v_add_u32_e32 v255, 0x38000, v255
	global_load_dwordx4 v[228:231], v252, s[30:31]
	global_load_dwordx4 v[232:235], v252, s[30:31] offset:256
	global_load_dwordx4 v[236:239], v254, s[30:31]
	global_load_dwordx4 v[240:243], v254, s[30:31] offset:256
	global_load_dwordx4 v[244:247], v255, s[30:31]
	global_load_dwordx4 v[248:251], v255, s[30:31] offset:256
	s_waitcnt vmcnt(12)
	v_lshlrev_b32_e32 v172, 16, v186
	v_and_b32_e32 v173, 0xffff0000, v186
	v_lshlrev_b32_e32 v186, 16, v187
	v_and_b32_e32 v187, 0xffff0000, v187
	v_lshlrev_b32_e32 v194, 16, v188
	v_and_b32_e32 v195, 0xffff0000, v188
	v_lshlrev_b32_e32 v188, 16, v189
	v_and_b32_e32 v189, 0xffff0000, v189
	v_lshlrev_b32_e32 v196, 16, v190
	v_and_b32_e32 v197, 0xffff0000, v190
	v_lshlrev_b32_e32 v190, 16, v191
	v_and_b32_e32 v191, 0xffff0000, v191
	v_pk_fma_f32 v[138:139], v[138:139], v[158:159], v[186:187]
	v_pk_fma_f32 v[172:173], v[136:137], v[156:157], v[172:173]
	v_pk_fma_f32 v[136:137], v[142:143], v[154:155], v[188:189]
	v_pk_fma_f32 v[140:141], v[140:141], v[152:153], v[194:195]
	v_lshlrev_b32_e32 v198, 16, v192
	v_and_b32_e32 v199, 0xffff0000, v192
	v_lshlrev_b32_e32 v192, 16, v193
	v_and_b32_e32 v193, 0xffff0000, v193
	v_pk_fma_f32 v[134:135], v[134:135], v[150:151], v[190:191]
	v_pk_fma_f32 v[132:133], v[132:133], v[148:149], v[196:197]
	v_mul_f32_e32 v142, v173, v173
	v_mul_f32_e32 v143, v139, v139
	v_mul_f32_e32 v175, v141, v141
	v_mul_f32_e32 v186, v137, v137
	v_pk_fma_f32 v[130:131], v[130:131], v[146:147], v[192:193]
	v_pk_fma_f32 v[128:129], v[128:129], v[144:145], v[198:199]
	v_mul_f32_e32 v187, v133, v133
	v_mul_f32_e32 v188, v135, v135
	v_fmac_f32_e32 v142, v172, v172
	v_fmac_f32_e32 v143, v138, v138
	v_fmac_f32_e32 v175, v140, v140
	v_fmac_f32_e32 v186, v136, v136
	v_mul_f32_e32 v189, v129, v129
	v_mul_f32_e32 v190, v131, v131
	v_fmac_f32_e32 v187, v132, v132
	v_fmac_f32_e32 v188, v134, v134
	v_add_f32_e32 v142, v142, v143
	v_add_f32_e32 v143, v175, v186
	v_fmac_f32_e32 v189, v128, v128
	v_fmac_f32_e32 v190, v130, v130
	v_add_f32_e32 v175, v187, v188
	v_add_f32_e32 v142, v142, v143
	v_add_f32_e32 v142, v142, v175
	v_add_f32_e32 v143, v189, v190
	v_add_f32_e32 v142, v143, v142
	ds_bpermute_b32 v143, v178, v142
	v_ashrrev_i32_e32 v175, 31, v174
	s_waitcnt lgkmcnt(0)
	v_add_f32_e32 v142, v142, v143
	ds_bpermute_b32 v143, v179, v142
	s_and_saveexec_b64 s[8:9], s[0:1]
	s_cbranch_execz .LBB0_803
	v_lshl_add_u64 v[186:187], v[174:175], 2, s[34:35]
	s_waitcnt lgkmcnt(0)
	v_add_f32_e32 v142, v142, v143
	global_atomic_add_f32 v[186:187], v142, off
.LBB0_803:
	s_or_b64 exec, exec, s[8:9]
	v_or_b32_e32 v142, 16, v174
	s_waitcnt lgkmcnt(0)
	v_lshl_add_u32 v143, v142, 12, v185
	v_lshrrev_b32_e32 v143, 1, v143
	s_waitcnt vmcnt(11)
	v_mov_b32_e32 v186, v202
	v_mov_b32_e32 v187, v203
	v_mov_b32_e32 v188, v204
	v_mov_b32_e32 v189, v205
	v_mov_b32_e32 v190, v206
	v_mov_b32_e32 v191, v207
	v_mov_b32_e32 v192, v208
	v_mov_b32_e32 v193, v209
	v_add_u32_e32 v255, 0x8000, v255
	global_load_dwordx4 v[202:205], v255, s[30:31]
	global_load_dwordx4 v[206:209], v255, s[30:31] offset:256
	v_lshlrev_b32_e32 v194, 16, v186
	v_and_b32_e32 v195, 0xffff0000, v186
	v_lshlrev_b32_e32 v186, 16, v187
	v_and_b32_e32 v187, 0xffff0000, v187
	v_lshlrev_b32_e32 v196, 16, v188
	v_and_b32_e32 v197, 0xffff0000, v188
	v_lshlrev_b32_e32 v188, 16, v189
	v_and_b32_e32 v189, 0xffff0000, v189
	v_lshlrev_b32_e32 v198, 16, v190
	v_and_b32_e32 v199, 0xffff0000, v190
	v_lshlrev_b32_e32 v190, 16, v191
	v_and_b32_e32 v191, 0xffff0000, v191
	v_pk_fma_f32 v[126:127], v[126:127], v[158:159], v[186:187]
	v_pk_fma_f32 v[124:125], v[124:125], v[156:157], v[194:195]
	v_pk_fma_f32 v[122:123], v[122:123], v[154:155], v[188:189]
	v_pk_fma_f32 v[120:121], v[120:121], v[152:153], v[196:197]
	v_lshlrev_b32_e32 v200, 16, v192
	v_and_b32_e32 v201, 0xffff0000, v192
	v_lshlrev_b32_e32 v192, 16, v193
	v_and_b32_e32 v193, 0xffff0000, v193
	v_pk_fma_f32 v[118:119], v[118:119], v[150:151], v[190:191]
	v_pk_fma_f32 v[116:117], v[116:117], v[148:149], v[198:199]
	v_mul_f32_e32 v143, v125, v125
	v_mul_f32_e32 v186, v127, v127
	v_mul_f32_e32 v187, v121, v121
	v_mul_f32_e32 v188, v123, v123
	v_pk_fma_f32 v[114:115], v[114:115], v[146:147], v[192:193]
	v_pk_fma_f32 v[112:113], v[112:113], v[144:145], v[200:201]
	v_mul_f32_e32 v189, v117, v117
	v_mul_f32_e32 v190, v119, v119
	v_fmac_f32_e32 v143, v124, v124
	v_fmac_f32_e32 v186, v126, v126
	v_fmac_f32_e32 v187, v120, v120
	v_fmac_f32_e32 v188, v122, v122
	v_mul_f32_e32 v191, v113, v113
	v_mul_f32_e32 v192, v115, v115
	v_fmac_f32_e32 v189, v116, v116
	v_fmac_f32_e32 v190, v118, v118
	v_add_f32_e32 v143, v143, v186
	v_add_f32_e32 v186, v187, v188
	v_fmac_f32_e32 v191, v112, v112
	v_fmac_f32_e32 v192, v114, v114
	v_add_f32_e32 v187, v189, v190
	v_add_f32_e32 v143, v143, v186
	v_add_f32_e32 v143, v143, v187
	v_add_f32_e32 v186, v191, v192
	v_add_f32_e32 v143, v186, v143
	ds_bpermute_b32 v186, v178, v143
	s_waitcnt lgkmcnt(0)
	v_add_f32_e32 v186, v143, v186
	ds_bpermute_b32 v187, v179, v186
	s_and_saveexec_b64 s[8:9], s[0:1]
	s_cbranch_execz .LBB0_805
	v_ashrrev_i32_e32 v143, 31, v142
	v_lshl_add_u64 v[142:143], v[142:143], 2, s[34:35]
	s_waitcnt lgkmcnt(0)
	v_add_f32_e32 v186, v186, v187
	global_atomic_add_f32 v[142:143], v186, off
.LBB0_805:
	s_or_b64 exec, exec, s[8:9]
	v_or_b32_e32 v142, 32, v174
	v_lshl_add_u32 v143, v142, 12, v185
	v_lshrrev_b32_e32 v143, 1, v143
	s_waitcnt lgkmcnt(0)
	s_waitcnt vmcnt(12)
	v_mov_b32_e32 v186, v210
	v_mov_b32_e32 v187, v211
	v_mov_b32_e32 v188, v212
	v_mov_b32_e32 v189, v213
	v_mov_b32_e32 v190, v214
	v_mov_b32_e32 v191, v215
	v_mov_b32_e32 v192, v216
	v_mov_b32_e32 v193, v217
	v_lshlrev_b32_e32 v194, 16, v186
	v_and_b32_e32 v195, 0xffff0000, v186
	v_lshlrev_b32_e32 v186, 16, v187
	v_and_b32_e32 v187, 0xffff0000, v187
	v_lshlrev_b32_e32 v196, 16, v188
	v_and_b32_e32 v197, 0xffff0000, v188
	v_lshlrev_b32_e32 v188, 16, v189
	v_and_b32_e32 v189, 0xffff0000, v189
	v_lshlrev_b32_e32 v198, 16, v190
	v_and_b32_e32 v199, 0xffff0000, v190
	v_lshlrev_b32_e32 v190, 16, v191
	v_and_b32_e32 v191, 0xffff0000, v191
	v_pk_fma_f32 v[110:111], v[110:111], v[158:159], v[186:187]
	v_pk_fma_f32 v[108:109], v[108:109], v[156:157], v[194:195]
	v_pk_fma_f32 v[106:107], v[106:107], v[154:155], v[188:189]
	v_pk_fma_f32 v[104:105], v[104:105], v[152:153], v[196:197]
	v_lshlrev_b32_e32 v200, 16, v192
	v_and_b32_e32 v201, 0xffff0000, v192
	v_lshlrev_b32_e32 v192, 16, v193
	v_and_b32_e32 v193, 0xffff0000, v193
	v_pk_fma_f32 v[102:103], v[102:103], v[150:151], v[190:191]
	v_pk_fma_f32 v[100:101], v[100:101], v[148:149], v[198:199]
	v_mul_f32_e32 v143, v109, v109
	v_mul_f32_e32 v186, v111, v111
	v_mul_f32_e32 v187, v105, v105
	v_mul_f32_e32 v188, v107, v107
	v_pk_fma_f32 v[98:99], v[98:99], v[146:147], v[192:193]
	v_pk_fma_f32 v[96:97], v[96:97], v[144:145], v[200:201]
	v_mul_f32_e32 v189, v101, v101
	v_mul_f32_e32 v190, v103, v103
	v_fmac_f32_e32 v143, v108, v108
	v_fmac_f32_e32 v186, v110, v110
	v_fmac_f32_e32 v187, v104, v104
	v_fmac_f32_e32 v188, v106, v106
	v_mul_f32_e32 v191, v97, v97
	v_mul_f32_e32 v192, v99, v99
	v_fmac_f32_e32 v189, v100, v100
	v_fmac_f32_e32 v190, v102, v102
	v_add_f32_e32 v143, v143, v186
	v_add_f32_e32 v186, v187, v188
	v_fmac_f32_e32 v191, v96, v96
	v_fmac_f32_e32 v192, v98, v98
	v_add_f32_e32 v187, v189, v190
	v_add_f32_e32 v143, v143, v186
	v_add_f32_e32 v143, v143, v187
	v_add_f32_e32 v186, v191, v192
	v_add_f32_e32 v143, v186, v143
	ds_bpermute_b32 v186, v178, v143
	s_waitcnt lgkmcnt(0)
	v_add_f32_e32 v186, v143, v186
	ds_bpermute_b32 v187, v179, v186
	s_and_saveexec_b64 s[8:9], s[0:1]
	s_cbranch_execz .LBB0_807
	v_ashrrev_i32_e32 v143, 31, v142
	v_lshl_add_u64 v[142:143], v[142:143], 2, s[34:35]
	s_waitcnt lgkmcnt(0)
	v_add_f32_e32 v186, v186, v187
	global_atomic_add_f32 v[142:143], v186, off
.LBB0_807:
	s_or_b64 exec, exec, s[8:9]
	v_or_b32_e32 v142, 48, v174
	v_lshl_add_u32 v143, v142, 12, v185
	v_lshrrev_b32_e32 v143, 1, v143
	s_waitcnt lgkmcnt(0)
	s_waitcnt vmcnt(11)
	v_mov_b32_e32 v186, v218
	v_mov_b32_e32 v187, v219
	v_mov_b32_e32 v188, v220
	v_mov_b32_e32 v189, v221
	v_mov_b32_e32 v190, v222
	v_mov_b32_e32 v191, v223
	v_mov_b32_e32 v192, v224
	v_mov_b32_e32 v193, v225
	v_lshlrev_b32_e32 v194, 16, v186
	v_and_b32_e32 v195, 0xffff0000, v186
	v_lshlrev_b32_e32 v186, 16, v187
	v_and_b32_e32 v187, 0xffff0000, v187
	v_lshlrev_b32_e32 v196, 16, v188
	v_and_b32_e32 v197, 0xffff0000, v188
	v_lshlrev_b32_e32 v188, 16, v189
	v_and_b32_e32 v189, 0xffff0000, v189
	v_lshlrev_b32_e32 v198, 16, v190
	v_and_b32_e32 v199, 0xffff0000, v190
	v_lshlrev_b32_e32 v190, 16, v191
	v_and_b32_e32 v191, 0xffff0000, v191
	v_pk_fma_f32 v[94:95], v[94:95], v[158:159], v[186:187]
	v_pk_fma_f32 v[92:93], v[92:93], v[156:157], v[194:195]
	v_pk_fma_f32 v[90:91], v[90:91], v[154:155], v[188:189]
	v_pk_fma_f32 v[88:89], v[88:89], v[152:153], v[196:197]
	v_lshlrev_b32_e32 v200, 16, v192
	v_and_b32_e32 v201, 0xffff0000, v192
	v_lshlrev_b32_e32 v192, 16, v193
	v_and_b32_e32 v193, 0xffff0000, v193
	v_pk_fma_f32 v[86:87], v[86:87], v[150:151], v[190:191]
	v_pk_fma_f32 v[84:85], v[84:85], v[148:149], v[198:199]
	v_mul_f32_e32 v143, v93, v93
	v_mul_f32_e32 v186, v95, v95
	v_mul_f32_e32 v187, v89, v89
	v_mul_f32_e32 v188, v91, v91
	v_pk_fma_f32 v[82:83], v[82:83], v[146:147], v[192:193]
	v_pk_fma_f32 v[80:81], v[80:81], v[144:145], v[200:201]
	v_mul_f32_e32 v189, v85, v85
	v_mul_f32_e32 v190, v87, v87
	v_fmac_f32_e32 v143, v92, v92
	v_fmac_f32_e32 v186, v94, v94
	v_fmac_f32_e32 v187, v88, v88
	v_fmac_f32_e32 v188, v90, v90
	v_mul_f32_e32 v191, v81, v81
	v_mul_f32_e32 v192, v83, v83
	v_fmac_f32_e32 v189, v84, v84
	v_fmac_f32_e32 v190, v86, v86
	v_add_f32_e32 v143, v143, v186
	v_add_f32_e32 v186, v187, v188
	v_fmac_f32_e32 v191, v80, v80
	v_fmac_f32_e32 v192, v82, v82
	v_add_f32_e32 v187, v189, v190
	v_add_f32_e32 v143, v143, v186
	v_add_f32_e32 v143, v143, v187
	v_add_f32_e32 v186, v191, v192
	v_add_f32_e32 v143, v186, v143
	ds_bpermute_b32 v186, v178, v143
	s_waitcnt lgkmcnt(0)
	v_add_f32_e32 v186, v143, v186
	ds_bpermute_b32 v187, v179, v186
	s_and_saveexec_b64 s[8:9], s[0:1]
	s_cbranch_execz .LBB0_809
	v_ashrrev_i32_e32 v143, 31, v142
	v_lshl_add_u64 v[142:143], v[142:143], 2, s[34:35]
	s_waitcnt lgkmcnt(0)
	v_add_f32_e32 v186, v186, v187
	global_atomic_add_f32 v[142:143], v186, off
.LBB0_809:
	s_or_b64 exec, exec, s[8:9]
	v_add_u32_e32 v142, 0x80, v174
	v_lshl_add_u32 v143, v142, 12, v185
	v_lshrrev_b32_e32 v143, 1, v143
	s_waitcnt lgkmcnt(0)
	s_waitcnt vmcnt(10)
	v_mov_b32_e32 v186, v228
	v_mov_b32_e32 v187, v229
	v_mov_b32_e32 v188, v230
	v_mov_b32_e32 v189, v231
	v_mov_b32_e32 v190, v232
	v_mov_b32_e32 v191, v233
	v_mov_b32_e32 v192, v234
	v_mov_b32_e32 v193, v235
	v_lshlrev_b32_e32 v194, 16, v186
	v_and_b32_e32 v195, 0xffff0000, v186
	v_lshlrev_b32_e32 v186, 16, v187
	v_and_b32_e32 v187, 0xffff0000, v187
	v_lshlrev_b32_e32 v196, 16, v188
	v_and_b32_e32 v197, 0xffff0000, v188
	v_lshlrev_b32_e32 v188, 16, v189
	v_and_b32_e32 v189, 0xffff0000, v189
	v_lshlrev_b32_e32 v198, 16, v190
	v_and_b32_e32 v199, 0xffff0000, v190
	v_lshlrev_b32_e32 v190, 16, v191
	v_and_b32_e32 v191, 0xffff0000, v191
	v_pk_fma_f32 v[66:67], v[66:67], v[158:159], v[186:187]
	v_pk_fma_f32 v[64:65], v[64:65], v[156:157], v[194:195]
	v_pk_fma_f32 v[62:63], v[62:63], v[154:155], v[188:189]
	v_pk_fma_f32 v[60:61], v[60:61], v[152:153], v[196:197]
	v_lshlrev_b32_e32 v200, 16, v192
	v_and_b32_e32 v201, 0xffff0000, v192
	v_lshlrev_b32_e32 v192, 16, v193
	v_and_b32_e32 v193, 0xffff0000, v193
	v_pk_fma_f32 v[54:55], v[54:55], v[150:151], v[190:191]
	v_pk_fma_f32 v[52:53], v[52:53], v[148:149], v[198:199]
	v_mul_f32_e32 v143, v65, v65
	v_mul_f32_e32 v186, v67, v67
	v_mul_f32_e32 v187, v61, v61
	v_mul_f32_e32 v188, v63, v63
	v_pk_fma_f32 v[50:51], v[50:51], v[146:147], v[192:193]
	v_pk_fma_f32 v[48:49], v[48:49], v[144:145], v[200:201]
	v_mul_f32_e32 v189, v53, v53
	v_mul_f32_e32 v190, v55, v55
	v_fmac_f32_e32 v143, v64, v64
	v_fmac_f32_e32 v186, v66, v66
	v_fmac_f32_e32 v187, v60, v60
	v_fmac_f32_e32 v188, v62, v62
	v_mul_f32_e32 v191, v49, v49
	v_mul_f32_e32 v192, v51, v51
	v_fmac_f32_e32 v189, v52, v52
	v_fmac_f32_e32 v190, v54, v54
	v_add_f32_e32 v143, v143, v186
	v_add_f32_e32 v186, v187, v188
	v_fmac_f32_e32 v191, v48, v48
	v_fmac_f32_e32 v192, v50, v50
	v_add_f32_e32 v187, v189, v190
	v_add_f32_e32 v143, v143, v186
	v_add_f32_e32 v143, v143, v187
	v_add_f32_e32 v186, v191, v192
	v_add_f32_e32 v143, v186, v143
	ds_bpermute_b32 v186, v178, v143
	s_waitcnt lgkmcnt(0)
	v_add_f32_e32 v186, v143, v186
	ds_bpermute_b32 v187, v179, v186
	s_and_saveexec_b64 s[8:9], s[0:1]
	s_cbranch_execz .LBB0_811
	v_ashrrev_i32_e32 v143, 31, v142
	v_lshl_add_u64 v[142:143], v[142:143], 2, s[34:35]
	s_waitcnt lgkmcnt(0)
	v_add_f32_e32 v186, v186, v187
	global_atomic_add_f32 v[142:143], v186, off
.LBB0_811:
	s_or_b64 exec, exec, s[8:9]
	v_add_u32_e32 v142, 0x90, v174
	v_lshl_add_u32 v143, v142, 12, v185
	v_lshrrev_b32_e32 v143, 1, v143
	s_waitcnt lgkmcnt(0)
	s_waitcnt vmcnt(9)
	v_mov_b32_e32 v186, v236
	v_mov_b32_e32 v187, v237
	v_mov_b32_e32 v188, v238
	v_mov_b32_e32 v189, v239
	v_mov_b32_e32 v190, v240
	v_mov_b32_e32 v191, v241
	v_mov_b32_e32 v192, v242
	v_mov_b32_e32 v193, v243
	v_lshlrev_b32_e32 v194, 16, v186
	v_and_b32_e32 v195, 0xffff0000, v186
	v_lshlrev_b32_e32 v186, 16, v187
	v_and_b32_e32 v187, 0xffff0000, v187
	v_lshlrev_b32_e32 v196, 16, v188
	v_and_b32_e32 v197, 0xffff0000, v188
	v_lshlrev_b32_e32 v188, 16, v189
	v_and_b32_e32 v189, 0xffff0000, v189
	v_lshlrev_b32_e32 v198, 16, v190
	v_and_b32_e32 v199, 0xffff0000, v190
	v_lshlrev_b32_e32 v190, 16, v191
	v_and_b32_e32 v191, 0xffff0000, v191
	v_pk_fma_f32 v[46:47], v[46:47], v[158:159], v[186:187]
	v_pk_fma_f32 v[44:45], v[44:45], v[156:157], v[194:195]
	v_pk_fma_f32 v[42:43], v[42:43], v[154:155], v[188:189]
	v_pk_fma_f32 v[40:41], v[40:41], v[152:153], v[196:197]
	v_lshlrev_b32_e32 v200, 16, v192
	v_and_b32_e32 v201, 0xffff0000, v192
	v_lshlrev_b32_e32 v192, 16, v193
	v_and_b32_e32 v193, 0xffff0000, v193
	v_pk_fma_f32 v[38:39], v[38:39], v[150:151], v[190:191]
	v_pk_fma_f32 v[36:37], v[36:37], v[148:149], v[198:199]
	v_mul_f32_e32 v143, v45, v45
	v_mul_f32_e32 v186, v47, v47
	v_mul_f32_e32 v187, v41, v41
	v_mul_f32_e32 v188, v43, v43
	v_pk_fma_f32 v[34:35], v[34:35], v[146:147], v[192:193]
	v_pk_fma_f32 v[32:33], v[32:33], v[144:145], v[200:201]
	v_mul_f32_e32 v189, v37, v37
	v_mul_f32_e32 v190, v39, v39
	v_fmac_f32_e32 v143, v44, v44
	v_fmac_f32_e32 v186, v46, v46
	v_fmac_f32_e32 v187, v40, v40
	v_fmac_f32_e32 v188, v42, v42
	v_mul_f32_e32 v191, v33, v33
	v_mul_f32_e32 v192, v35, v35
	v_fmac_f32_e32 v189, v36, v36
	v_fmac_f32_e32 v190, v38, v38
	v_add_f32_e32 v143, v143, v186
	v_add_f32_e32 v186, v187, v188
	v_fmac_f32_e32 v191, v32, v32
	v_fmac_f32_e32 v192, v34, v34
	v_add_f32_e32 v187, v189, v190
	v_add_f32_e32 v143, v143, v186
	v_add_f32_e32 v143, v143, v187
	v_add_f32_e32 v186, v191, v192
	v_add_f32_e32 v143, v186, v143
	ds_bpermute_b32 v186, v178, v143
	s_waitcnt lgkmcnt(0)
	v_add_f32_e32 v186, v143, v186
	ds_bpermute_b32 v187, v179, v186
	s_and_saveexec_b64 s[8:9], s[0:1]
	s_cbranch_execz .LBB0_813
	v_ashrrev_i32_e32 v143, 31, v142
	v_lshl_add_u64 v[142:143], v[142:143], 2, s[34:35]
	s_waitcnt lgkmcnt(0)
	v_add_f32_e32 v186, v186, v187
	global_atomic_add_f32 v[142:143], v186, off
.LBB0_813:
	s_or_b64 exec, exec, s[8:9]
	v_add_u32_e32 v142, 0xa0, v174
	v_lshl_add_u32 v143, v142, 12, v185
	v_lshrrev_b32_e32 v143, 1, v143
	s_waitcnt lgkmcnt(0)
	s_waitcnt vmcnt(8)
	v_mov_b32_e32 v186, v244
	v_mov_b32_e32 v187, v245
	v_mov_b32_e32 v188, v246
	v_mov_b32_e32 v189, v247
	v_mov_b32_e32 v190, v248
	v_mov_b32_e32 v191, v249
	v_mov_b32_e32 v192, v250
	v_mov_b32_e32 v193, v251
	v_lshlrev_b32_e32 v194, 16, v186
	v_and_b32_e32 v195, 0xffff0000, v186
	v_lshlrev_b32_e32 v186, 16, v187
	v_and_b32_e32 v187, 0xffff0000, v187
	v_lshlrev_b32_e32 v196, 16, v188
	v_and_b32_e32 v197, 0xffff0000, v188
	v_lshlrev_b32_e32 v188, 16, v189
	v_and_b32_e32 v189, 0xffff0000, v189
	v_lshlrev_b32_e32 v198, 16, v190
	v_and_b32_e32 v199, 0xffff0000, v190
	v_lshlrev_b32_e32 v190, 16, v191
	v_and_b32_e32 v191, 0xffff0000, v191
	v_pk_fma_f32 v[30:31], v[30:31], v[158:159], v[186:187]
	v_pk_fma_f32 v[28:29], v[28:29], v[156:157], v[194:195]
	v_pk_fma_f32 v[26:27], v[26:27], v[154:155], v[188:189]
	v_pk_fma_f32 v[24:25], v[24:25], v[152:153], v[196:197]
	v_lshlrev_b32_e32 v200, 16, v192
	v_and_b32_e32 v201, 0xffff0000, v192
	v_lshlrev_b32_e32 v192, 16, v193
	v_and_b32_e32 v193, 0xffff0000, v193
	v_pk_fma_f32 v[22:23], v[22:23], v[150:151], v[190:191]
	v_pk_fma_f32 v[20:21], v[20:21], v[148:149], v[198:199]
	v_mul_f32_e32 v143, v29, v29
	v_mul_f32_e32 v186, v31, v31
	v_mul_f32_e32 v187, v25, v25
	v_mul_f32_e32 v188, v27, v27
	v_pk_fma_f32 v[18:19], v[18:19], v[146:147], v[192:193]
	v_pk_fma_f32 v[16:17], v[16:17], v[144:145], v[200:201]
	v_mul_f32_e32 v189, v21, v21
	v_mul_f32_e32 v190, v23, v23
	v_fmac_f32_e32 v143, v28, v28
	v_fmac_f32_e32 v186, v30, v30
	v_fmac_f32_e32 v187, v24, v24
	v_fmac_f32_e32 v188, v26, v26
	v_mul_f32_e32 v191, v17, v17
	v_mul_f32_e32 v192, v19, v19
	v_fmac_f32_e32 v189, v20, v20
	v_fmac_f32_e32 v190, v22, v22
	v_add_f32_e32 v143, v143, v186
	v_add_f32_e32 v186, v187, v188
	v_fmac_f32_e32 v191, v16, v16
	v_fmac_f32_e32 v192, v18, v18
	v_add_f32_e32 v187, v189, v190
	v_add_f32_e32 v143, v143, v186
	v_add_f32_e32 v143, v143, v187
	v_add_f32_e32 v186, v191, v192
	v_add_f32_e32 v143, v186, v143
	ds_bpermute_b32 v186, v178, v143
	s_waitcnt lgkmcnt(0)
	v_add_f32_e32 v186, v143, v186
	ds_bpermute_b32 v187, v179, v186
	s_and_saveexec_b64 s[8:9], s[0:1]
	s_cbranch_execz .LBB0_815
	v_ashrrev_i32_e32 v143, 31, v142
	v_lshl_add_u64 v[142:143], v[142:143], 2, s[34:35]
	s_waitcnt lgkmcnt(0)
	v_add_f32_e32 v186, v186, v187
	global_atomic_add_f32 v[142:143], v186, off
.LBB0_815:
	s_or_b64 exec, exec, s[8:9]
	v_add_u32_e32 v142, 0xb0, v174
	v_lshl_add_u32 v143, v142, 12, v185
	v_lshrrev_b32_e32 v143, 1, v143
	s_waitcnt lgkmcnt(0)
	s_waitcnt vmcnt(6)
	v_mov_b32_e32 v186, v202
	v_mov_b32_e32 v187, v203
	v_mov_b32_e32 v188, v204
	v_mov_b32_e32 v189, v205
	v_mov_b32_e32 v190, v206
	v_mov_b32_e32 v191, v207
	v_mov_b32_e32 v192, v208
	v_mov_b32_e32 v193, v209
	v_lshlrev_b32_e32 v194, 16, v186
	v_and_b32_e32 v195, 0xffff0000, v186
	v_lshlrev_b32_e32 v186, 16, v187
	v_and_b32_e32 v187, 0xffff0000, v187
	v_lshlrev_b32_e32 v196, 16, v188
	v_and_b32_e32 v197, 0xffff0000, v188
	v_lshlrev_b32_e32 v188, 16, v189
	v_and_b32_e32 v189, 0xffff0000, v189
	v_lshlrev_b32_e32 v198, 16, v190
	v_and_b32_e32 v199, 0xffff0000, v190
	v_lshlrev_b32_e32 v190, 16, v191
	v_and_b32_e32 v191, 0xffff0000, v191
	v_lshlrev_b32_e32 v200, 16, v192
	v_and_b32_e32 v201, 0xffff0000, v192
	v_lshlrev_b32_e32 v192, 16, v193
	v_and_b32_e32 v193, 0xffff0000, v193
	v_pk_fma_f32 v[14:15], v[14:15], v[158:159], v[186:187]
	v_pk_fma_f32 v[12:13], v[12:13], v[156:157], v[194:195]
	v_pk_fma_f32 v[10:11], v[10:11], v[154:155], v[188:189]
	v_pk_fma_f32 v[8:9], v[8:9], v[152:153], v[196:197]
	v_pk_fma_f32 v[6:7], v[6:7], v[150:151], v[190:191]
	v_pk_fma_f32 v[4:5], v[4:5], v[148:149], v[198:199]
	v_pk_fma_f32 v[2:3], v[2:3], v[146:147], v[192:193]
	v_pk_fma_f32 v[0:1], v[0:1], v[144:145], v[200:201]
	v_mul_f32_e32 v143, v13, v13
	v_mul_f32_e32 v144, v15, v15
	v_mul_f32_e32 v145, v9, v9
	v_mul_f32_e32 v146, v11, v11
	v_mul_f32_e32 v147, v5, v5
	v_mul_f32_e32 v148, v7, v7
	v_fmac_f32_e32 v143, v12, v12
	v_fmac_f32_e32 v144, v14, v14
	v_fmac_f32_e32 v145, v8, v8
	v_fmac_f32_e32 v146, v10, v10
	v_mul_f32_e32 v149, v1, v1
	v_mul_f32_e32 v150, v3, v3
	v_fmac_f32_e32 v147, v4, v4
	v_fmac_f32_e32 v148, v6, v6
	v_add_f32_e32 v143, v143, v144
	v_add_f32_e32 v144, v145, v146
	v_fmac_f32_e32 v149, v0, v0
	v_fmac_f32_e32 v150, v2, v2
	v_add_f32_e32 v145, v147, v148
	v_add_f32_e32 v143, v143, v144
	v_add_f32_e32 v143, v143, v145
	v_add_f32_e32 v144, v149, v150
	v_add_f32_e32 v143, v144, v143
	ds_bpermute_b32 v144, v178, v143
	s_waitcnt lgkmcnt(0)
	v_add_f32_e32 v144, v143, v144
	ds_bpermute_b32 v145, v179, v144
	s_and_saveexec_b64 s[8:9], s[0:1]
	s_cbranch_execz .LBB0_817
	v_ashrrev_i32_e32 v143, 31, v142
	v_lshl_add_u64 v[142:143], v[142:143], 2, s[34:35]
	s_waitcnt lgkmcnt(0)
	v_add_f32_e32 v144, v144, v145
	global_atomic_add_f32 v[142:143], v144, off

	.amdhsa_kernel _Z14fwd_megakernel6Params
		.amdhsa_group_segment_fixed_size 0
		.amdhsa_private_segment_fixed_size 0
		.amdhsa_kernarg_size 424
		.amdhsa_user_sgpr_count 2
		.amdhsa_user_sgpr_dispatch_ptr 0
		.amdhsa_user_sgpr_queue_ptr 0
		.amdhsa_user_sgpr_kernarg_segment_ptr 1
		.amdhsa_user_sgpr_dispatch_id 0
		.amdhsa_user_sgpr_kernarg_preload_length 0
		.amdhsa_user_sgpr_kernarg_preload_offset 0
		.amdhsa_user_sgpr_private_segment_size 0
		.amdhsa_uses_dynamic_stack 0
		.amdhsa_enable_private_segment 0
		.amdhsa_system_sgpr_workgroup_id_x 1
		.amdhsa_system_sgpr_workgroup_id_y 0
		.amdhsa_system_sgpr_workgroup_id_z 0
		.amdhsa_system_sgpr_workgroup_info 0
		.amdhsa_system_vgpr_workitem_id 2
		.amdhsa_next_free_vgpr 256
		.amdhsa_next_free_sgpr 98
		.amdhsa_accum_offset 256
		.amdhsa_reserve_vcc 1
		.amdhsa_float_round_mode_32 0
		.amdhsa_float_round_mode_16_64 0
		.amdhsa_float_denorm_mode_32 3
		.amdhsa_float_denorm_mode_16_64 3
		.amdhsa_dx10_clamp 1
		.amdhsa_ieee_mode 1
		.amdhsa_fp16_overflow 0
		.amdhsa_tg_split 0
		.amdhsa_exception_fp_ieee_invalid_op 0
		.amdhsa_exception_fp_denorm_src 0
		.amdhsa_exception_fp_ieee_div_zero 0
		.amdhsa_exception_fp_ieee_overflow 0
		.amdhsa_exception_fp_ieee_underflow 0
		.amdhsa_exception_fp_ieee_inexact 0
		.amdhsa_exception_int_div_zero 0
	.end_amdhsa_kernel

amdhsa.kernels:
  - .agpr_count:     0
    .args:
      - .offset:         0
        .size:           168
        .value_kind:     by_value
      - .offset:         168
        .size:           4
        .value_kind:     hidden_block_count_x
      - .offset:         172
        .size:           4
        .value_kind:     hidden_block_count_y
      - .offset:         176
        .size:           4
        .value_kind:     hidden_block_count_z
      - .offset:         180
        .size:           2
        .value_kind:     hidden_group_size_x
      - .offset:         182
        .size:           2
        .value_kind:     hidden_group_size_y
      - .offset:         184
        .size:           2
        .value_kind:     hidden_group_size_z
      - .offset:         186
        .size:           2
        .value_kind:     hidden_remainder_x
      - .offset:         188
        .size:           2
        .value_kind:     hidden_remainder_y
      - .offset:         190
        .size:           2
        .value_kind:     hidden_remainder_z
      - .offset:         208
        .size:           8
        .value_kind:     hidden_global_offset_x
      - .offset:         216
        .size:           8
        .value_kind:     hidden_global_offset_y
      - .offset:         224
        .size:           8
        .value_kind:     hidden_global_offset_z
      - .offset:         232
        .size:           2
        .value_kind:     hidden_grid_dims
      - .offset:         256
        .size:           8
        .value_kind:     hidden_multigrid_sync_arg
      - .offset:         288
        .size:           4
        .value_kind:     hidden_dynamic_lds_size
    .group_segment_fixed_size: 0
    .kernarg_segment_align: 8
    .kernarg_segment_size: 424
    .language:       OpenCL C
    .language_version:
      - 2
      - 0
    .max_flat_workgroup_size: 512
    .name:           _Z14fwd_megakernel6Params
    .private_segment_fixed_size: 0
    .sgpr_count:     104
    .sgpr_spill_count: 11
    .symbol:         _Z14fwd_megakernel6Params.kd
    .uniform_work_group_size: 1
    .uses_dynamic_stack: false
    .vgpr_count:     256
    .vgpr_spill_count: 0
    .wavefront_size: 64
